# prompt attention units remapped so that workgroups of one XCD share (batch, head)
# speedup vs baseline: 1.0008x; 1.0008x over previous
.LBB0_1548:
	s_or_b64 exec, exec, s[0:1]
	v_mbcnt_lo_u32_b32 v0, -1, 0
	v_mbcnt_hi_u32_b32 v2, -1, v0
	v_and_b32_e32 v0, 64, v2
	v_add_u32_e32 v3, 64, v0
	v_xor_b32_e32 v0, 1, v2
	v_cmp_lt_i32_e32 vcc, v0, v3
	s_and_b32 s15, s61, 0xffffffc0
	s_cmpk_lt_i32 s33, 0x100
	v_cndmask_b32_e32 v0, v2, v0, vcc
	v_lshlrev_b32_e32 v194, 2, v0
	ds_bpermute_b32 v0, v194, v5
	v_max_f32_e32 v5, v5, v5
	ds_bpermute_b32 v1, v194, v4
	v_max_f32_e32 v4, v4, v4
	s_cselect_b64 s[4:5], -1, 0
	s_waitcnt lgkmcnt(1)
	v_max_f32_e32 v0, v0, v0
	v_max_f32_e32 v0, v5, v0
	v_xor_b32_e32 v5, 2, v2
	v_cmp_lt_i32_e32 vcc, v5, v3
	s_waitcnt lgkmcnt(0)
	v_max_f32_e32 v1, v1, v1
	v_max_f32_e32 v1, v4, v1
	v_cndmask_b32_e32 v5, v2, v5, vcc
	v_lshlrev_b32_e32 v195, 2, v5
	ds_bpermute_b32 v5, v195, v0
	ds_bpermute_b32 v4, v195, v1
	s_cmpk_gt_i32 s33, 0xff
	s_mov_b32 s7, 0
	s_waitcnt lgkmcnt(1)
	v_max_f32_e32 v5, v5, v5
	v_max_f32_e32 v0, v0, v5
	v_xor_b32_e32 v5, 4, v2
	v_cmp_lt_i32_e32 vcc, v5, v3
	s_waitcnt lgkmcnt(0)
	v_max_f32_e32 v4, v4, v4
	v_max_f32_e32 v1, v1, v4
	v_cndmask_b32_e32 v5, v2, v5, vcc
	v_lshlrev_b32_e32 v196, 2, v5
	ds_bpermute_b32 v5, v196, v0
	ds_bpermute_b32 v4, v196, v1
	s_waitcnt lgkmcnt(1)
	v_max_f32_e32 v5, v5, v5
	v_max_f32_e32 v0, v0, v5
	v_xor_b32_e32 v5, 8, v2
	v_cmp_lt_i32_e32 vcc, v5, v3
	s_waitcnt lgkmcnt(0)
	v_max_f32_e32 v4, v4, v4
	v_max_f32_e32 v1, v1, v4
	v_cndmask_b32_e32 v5, v2, v5, vcc
	v_lshlrev_b32_e32 v197, 2, v5
	ds_bpermute_b32 v5, v197, v0
	ds_bpermute_b32 v4, v197, v1
	s_waitcnt lgkmcnt(1)
	v_max_f32_e32 v5, v5, v5
	v_max_f32_e32 v0, v0, v5
	v_xor_b32_e32 v5, 16, v2
	v_cmp_lt_i32_e32 vcc, v5, v3
	s_waitcnt lgkmcnt(0)
	v_max_f32_e32 v4, v4, v4
	v_max_f32_e32 v4, v1, v4
	v_cndmask_b32_e32 v5, v2, v5, vcc
	v_lshlrev_b32_e32 v198, 2, v5
	ds_bpermute_b32 v5, v198, v0
	ds_bpermute_b32 v6, v198, v4
	s_waitcnt lgkmcnt(1)
	v_max_f32_e32 v1, v5, v5
	v_max_f32_e32 v1, v0, v1
	s_waitcnt lgkmcnt(0)
	v_max_f32_e32 v0, v6, v6
	v_max_f32_e32 v0, v4, v0
	v_xor_b32_e32 v4, 32, v2
	v_cmp_lt_i32_e32 vcc, v4, v3
	s_nop 1
	v_cndmask_b32_e32 v2, v2, v4, vcc
	v_lshlrev_b32_e32 v199, 2, v2
	ds_bpermute_b32 v3, v199, v1
	ds_bpermute_b32 v2, v199, v0
	s_cbranch_scc1 .LBB0_1577
	v_ashrrev_i32_e32 v20, 5, v16
	v_lshlrev_b32_e32 v128, 3, v20
	v_ashrrev_i32_e32 v129, 31, v128
	v_lshl_add_u64 v[18:19], v[128:129], 2, s[86:87]
	s_mov_b64 s[0:1], 0x282ca000
	v_add_u32_e32 v17, s15, v16
	v_lshl_add_u64 v[130:131], v[18:19], 0, s[0:1]
	s_mov_b32 s0, 0x2aaaaaab
	v_mul_hi_i32 v18, v17, s0
	v_lshrrev_b32_e32 v19, 31, v18
	v_ashrrev_i32_e32 v18, 1, v18
	v_add_u32_e32 v18, v18, v19
	v_mul_lo_u32 v19, v18, 12
	s_movk_i32 s1, 0x300
	s_movk_i32 s28, 0xd0
	v_sub_u32_e32 v19, v17, v19
	v_mul_lo_u32 v21, v18, s1
	v_mul_lo_u32 v125, v18, s28
	v_add_u32_e32 v18, 0x200, v17
	v_lshl_add_u32 v132, v19, 3, v21
	v_lshlrev_b32_e32 v190, 4, v19
	v_mul_hi_i32 v19, v18, s0
	v_lshrrev_b32_e32 v21, 31, v19
	v_ashrrev_i32_e32 v19, 1, v19
	v_add_u32_e32 v19, v19, v21
	v_mul_lo_u32 v21, v19, 12
	v_sub_u32_e32 v21, v18, v21
	v_mul_lo_u32 v22, v19, s1
	v_mul_lo_u32 v191, v19, s28
	v_add_u32_e32 v19, 0x400, v17
	v_lshl_add_u32 v134, v21, 3, v22
	v_lshlrev_b32_e32 v192, 4, v21
	v_mul_hi_i32 v21, v19, s0
	v_lshrrev_b32_e32 v22, 31, v21
	v_ashrrev_i32_e32 v21, 1, v21
	v_add_u32_e32 v21, v21, v22
	s_add_u32 s8, s86, 0x15e41000
	v_mul_lo_u32 v22, v21, 12
	s_addc_u32 s9, s87, 0
	v_sub_u32_e32 v19, v19, v22
	v_mul_lo_u32 v22, v21, s1
	s_add_u32 s14, s86, 0x14dc1000
	v_lshl_add_u32 v136, v19, 3, v22
	v_lshlrev_b32_e32 v200, 4, v19
	v_and_b32_e32 v19, 7, v16
	s_addc_u32 s24, s87, 0
	s_lshl_b32 s25, s91, 5
	v_mul_lo_u32 v193, v21, s28
	v_lshlrev_b32_e32 v21, 3, v19
	v_ashrrev_i32_e32 v17, 3, v17
	s_movk_i32 s0, 0x90
	s_add_u32 s26, s86, 0x17701000
	v_lshl_or_b32 v138, v17, 9, v21
	v_mul_lo_u32 v201, v17, s0
	v_ashrrev_i32_e32 v17, 3, v18
	s_addc_u32 s27, s87, 0
	v_lshl_or_b32 v140, v17, 9, v21
	v_mul_lo_u32 v202, v17, s0
	v_lshlrev_b32_e32 v142, 2, v20
	v_lshrrev_b32_e32 v17, 2, v16
	s_add_u32 s10, s86, 0x281c2000
	v_and_or_b32 v17, v17, 3, v142
	s_addc_u32 s11, s87, 0
	v_mul_lo_u32 v17, v17, s0
	s_lshl_b32 s0, s91, 7
	s_add_i32 s0, s0, 0
	v_and_b32_e32 v124, 31, v16
	v_lshlrev_b32_e32 v20, 4, v20
	s_add_i32 s0, s0, 0x16000
	v_ashrrev_i32_e32 v143, 31, v142
	v_lshl_add_u32 v206, v124, 2, s0
	v_add_u32_e32 v207, s0, v20
	v_lshlrev_b64 v[144:145], 10, v[142:143]
	s_mov_b64 s[0:1], 0x2000
	v_lshl_add_u64 v[152:153], v[144:145], 0, s[0:1]
	s_mov_b64 s[0:1], 0x2400
	v_lshl_add_u64 v[154:155], v[144:145], 0, s[0:1]
	s_mov_b64 s[0:1], 0x2800
	v_lshl_add_u64 v[156:157], v[144:145], 0, s[0:1]
	s_mov_b64 s[0:1], 0x2c00
	v_and_b32_e32 v18, 16, v16
	v_lshlrev_b32_e32 v21, 2, v16
	v_lshl_add_u64 v[158:159], v[144:145], 0, s[0:1]
	s_mov_b64 s[0:1], 0x4000
	s_waitcnt lgkmcnt(1)
	v_max_f32_e32 v3, v3, v3
	v_max_f32_e32 v1, v1, v1
	v_and_or_b32 v18, v21, 12, v18
	v_lshl_add_u64 v[160:161], v[144:145], 0, s[0:1]
	s_mov_b64 s[0:1], 0x4400
	v_max_f32_e32 v1, v1, v3
	s_waitcnt lgkmcnt(0)
	v_max_f32_e32 v2, v2, v2
	v_max_f32_e32 v0, v0, v0
	v_lshlrev_b32_e32 v18, 1, v18
	v_cmp_gt_u32_e64 s[2:3], 32, v16
	v_or_b32_e32 v16, 1, v142
	v_lshl_add_u64 v[162:163], v[144:145], 0, s[0:1]
	s_mov_b64 s[0:1], 0x4800
	v_mul_f32_e32 v1, 0x411cc471, v1
	v_max_f32_e32 v0, v0, v2
	v_add3_u32 v204, 0, v17, v18
	v_ashrrev_i32_e32 v17, 31, v16
	v_lshl_add_u64 v[164:165], v[144:145], 0, s[0:1]
	s_mov_b64 s[0:1], 0x4c00
	v_mul_f32_e32 v0, v1, v0
	v_lshlrev_b64 v[146:147], 10, v[16:17]
	v_or_b32_e32 v16, 2, v142
	v_lshl_add_u64 v[166:167], v[144:145], 0, s[0:1]
	s_mov_b64 s[0:1], 0x6000
	v_mul_f32_e32 v0, 0x3fb8aa3b, v0
	v_mov_b32_e32 v1, 0x3d4ccccd
	v_ashrrev_i32_e32 v17, 31, v16
	v_lshl_add_u64 v[168:169], v[144:145], 0, s[0:1]
	s_mov_b64 s[0:1], 0x6400
	v_fmac_f32_e32 v1, 0x3f828f5c, v0
	v_lshlrev_b64 v[148:149], 10, v[16:17]
	v_or_b32_e32 v16, 3, v142
	v_lshl_add_u64 v[170:171], v[144:145], 0, s[0:1]
	s_mov_b64 s[0:1], 0x6800
	v_xor_b32_e32 v0, 0x80000000, v1
	v_mov_b32_e32 v127, 0
	s_add_u32 s29, s86, 0x18fc1000
	v_ashrrev_i32_e32 v17, 31, v16
	v_lshl_add_u64 v[172:173], v[144:145], 0, s[0:1]
	s_mov_b64 s[0:1], 0x6c00
	v_mov_b32_e32 v1, v0
	v_mov_b32_e32 v2, v0
	v_mov_b32_e32 v3, v0
	v_mov_b32_e32 v4, v0
	v_mov_b32_e32 v5, v0
	v_mov_b32_e32 v6, v0
	v_mov_b32_e32 v7, v0
	v_mov_b32_e32 v8, v0
	v_mov_b32_e32 v9, v0
	v_mov_b32_e32 v10, v0
	v_mov_b32_e32 v11, v0
	v_mov_b32_e32 v12, v0
	v_mov_b32_e32 v13, v0
	v_mov_b32_e32 v14, v0
	v_mov_b32_e32 v15, v0
	v_mov_b32_e32 v133, v127
	v_mov_b32_e32 v135, v127
	v_mov_b32_e32 v137, v127
	v_mov_b32_e32 v139, v127
	v_mov_b32_e32 v141, v127
	v_add_u32_e32 v203, 0, v20
	v_lshl_add_u32 v205, v19, 4, 0
	s_addc_u32 s30, s87, 0
	v_lshlrev_b64 v[150:151], 10, v[16:17]
	v_lshl_add_u64 v[174:175], v[144:145], 0, s[0:1]
	s_movk_i32 s31, 0x600
	v_mov_b32_e32 v143, 0x358637bd
	s_mov_b32 s34, 0xf800000
	v_mov_b32_e32 v208, 0x260
	s_movk_i32 s35, 0x7fff
	v_lshlrev_b32_e32 v126, 1, v124
	v_mov_b32_e32 v209, 0x600
	s_mov_b32 s36, s33
	s_cmp_lg_u32 s57, 0x100
	s_cbranch_scc1 .Lmy_xcd_skip
	s_and_b32 s36, s33, 7
	s_lshl_b32 s36, s36, 5
	s_lshr_b32 s0, s33, 3
	s_or_b32 s36, s36, s0
.Lmy_xcd_skip:
	s_branch .LBB0_1551
